# diff-attention combine: 16-lane butterflies via DPP instead of ds_bpermute
# baseline (speedup 1.0000x reference)
.LBB0_571:
	v_add_u32_e32 v15, s20, v12
	v_mad_i64_i32 v[32:33], s[0:1], v15, s21, v[8:9]
	v_add_u32_e32 v15, 4, v15
	global_load_dwordx4 v[16:19], v[32:33], off
	global_load_dwordx4 v[20:23], v[32:33], off offset:1024
	v_mad_i64_i32 v[34:35], s[0:1], v15, s21, v[8:9]
	global_load_dwordx4 v[24:27], v[34:35], off
	global_load_dwordx4 v[28:31], v[34:35], off offset:1024
	s_add_i32 s20, s20, 8
	s_cmp_lg_u32 s20, 32
	s_waitcnt vmcnt(3)
	v_lshlrev_b32_e32 v36, 16, v16
	v_and_b32_e32 v37, 0xffff0000, v16
	v_lshlrev_b32_e32 v16, 16, v17
	v_and_b32_e32 v17, 0xffff0000, v17
	s_waitcnt vmcnt(2)
	v_lshlrev_b32_e32 v38, 16, v20
	v_and_b32_e32 v39, 0xffff0000, v20
	v_lshlrev_b32_e32 v20, 16, v21
	v_and_b32_e32 v21, 0xffff0000, v21
	v_lshlrev_b32_e32 v40, 16, v18
	v_and_b32_e32 v41, 0xffff0000, v18
	v_lshlrev_b32_e32 v18, 16, v19
	v_and_b32_e32 v19, 0xffff0000, v19
	v_lshlrev_b32_e32 v42, 16, v22
	v_and_b32_e32 v43, 0xffff0000, v22
	v_lshlrev_b32_e32 v22, 16, v23
	v_and_b32_e32 v23, 0xffff0000, v23
	v_pk_fma_f32 v[16:17], s[10:11], v[20:21], v[16:17]
	v_pk_fma_f32 v[20:21], s[6:7], v[38:39], v[36:37] neg_lo:[1,0,0] neg_hi:[1,0,0]
	v_pk_fma_f32 v[18:19], s[10:11], v[22:23], v[18:19]
	v_pk_fma_f32 v[22:23], s[6:7], v[42:43], v[40:41] neg_lo:[1,0,0] neg_hi:[1,0,0]
	s_waitcnt vmcnt(1)
	v_lshlrev_b32_e32 v36, 16, v24
	v_and_b32_e32 v37, 0xffff0000, v24
	v_lshlrev_b32_e32 v24, 16, v25
	v_and_b32_e32 v25, 0xffff0000, v25
	s_waitcnt vmcnt(0)
	v_lshlrev_b32_e32 v38, 16, v28
	v_and_b32_e32 v39, 0xffff0000, v28
	v_lshlrev_b32_e32 v28, 16, v29
	v_and_b32_e32 v29, 0xffff0000, v29
	v_pk_mul_f32 v[44:45], v[16:17], v[16:17]
	v_pk_mul_f32 v[46:47], v[20:21], v[20:21]
	v_lshlrev_b32_e32 v40, 16, v26
	v_and_b32_e32 v41, 0xffff0000, v26
	v_lshlrev_b32_e32 v26, 16, v27
	v_and_b32_e32 v27, 0xffff0000, v27
	v_lshlrev_b32_e32 v42, 16, v30
	v_and_b32_e32 v43, 0xffff0000, v30
	v_lshlrev_b32_e32 v30, 16, v31
	v_and_b32_e32 v31, 0xffff0000, v31
	v_pk_mul_f32 v[48:49], v[18:19], v[18:19]
	v_pk_mul_f32 v[50:51], v[22:23], v[22:23]
	v_pk_fma_f32 v[24:25], s[10:11], v[28:29], v[24:25]
	v_pk_fma_f32 v[28:29], s[6:7], v[38:39], v[36:37] neg_lo:[1,0,0] neg_hi:[1,0,0]
	v_pk_mov_b32 v[36:37], v[46:47], v[44:45] op_sel:[1,0]
	v_mov_b32_e32 v47, v45
	v_pk_fma_f32 v[26:27], s[10:11], v[30:31], v[26:27]
	v_pk_fma_f32 v[30:31], s[6:7], v[42:43], v[40:41] neg_lo:[1,0,0] neg_hi:[1,0,0]
	v_mov_b32_e32 v38, v48
	v_mov_b32_e32 v39, v50
	v_mov_b32_e32 v50, v49
	v_pk_mul_f32 v[40:41], v[24:25], v[24:25]
	v_pk_mul_f32 v[42:43], v[28:29], v[28:29]
	v_pk_add_f32 v[36:37], v[36:37], v[46:47]
	v_pk_mul_f32 v[44:45], v[26:27], v[26:27]
	v_pk_mul_f32 v[48:49], v[30:31], v[30:31]
	v_pk_add_f32 v[38:39], v[38:39], v[50:51]
	v_pk_mov_b32 v[46:47], v[42:43], v[40:41] op_sel:[1,0]
	v_mov_b32_e32 v43, v41
	v_add_f32_e32 v15, v36, v37
	v_mov_b32_e32 v40, v44
	v_mov_b32_e32 v41, v48
	v_mov_b32_e32 v48, v45
	v_pk_add_f32 v[36:37], v[46:47], v[42:43]
	v_add_f32_e32 v15, v39, v15
	v_pk_add_f32 v[40:41], v[40:41], v[48:49]
	v_add_f32_e32 v36, v36, v37
	v_add_f32_e32 v15, v38, v15
	v_add_f32_e32 v36, v41, v36
	v_add_f32_e32 v36, v40, v36
	s_nop 1
	v_add_f32_dpp v15, v15, v15 quad_perm:[1,0,3,2] row_mask:0xf bank_mask:0xf
	v_add_f32_dpp v36, v36, v36 quad_perm:[1,0,3,2] row_mask:0xf bank_mask:0xf
	s_nop 0
	v_add_f32_dpp v15, v15, v15 quad_perm:[2,3,0,1] row_mask:0xf bank_mask:0xf
	v_add_f32_dpp v36, v36, v36 quad_perm:[2,3,0,1] row_mask:0xf bank_mask:0xf
	s_nop 0
	v_add_f32_dpp v15, v15, v15 row_half_mirror row_mask:0xf bank_mask:0xf
	v_add_f32_dpp v36, v36, v36 row_half_mirror row_mask:0xf bank_mask:0xf
	s_nop 0
	v_add_f32_dpp v15, v15, v15 row_mirror row_mask:0xf bank_mask:0xf
	v_add_f32_dpp v36, v36, v36 row_mirror row_mask:0xf bank_mask:0xf
	s_nop 0
	v_fmamk_f32 v15, v15, 0x3c000000, v13
	v_mul_f32_e32 v37, 0x4f800000, v15
	v_cmp_gt_f32_e32 vcc, s28, v15
	v_fmamk_f32 v36, v36, 0x3c000000, v13
	v_cmp_gt_f32_e64 s[0:1], s28, v36
	v_cndmask_b32_e32 v15, v15, v37, vcc
	v_mul_f32_e32 v37, 0x4f800000, v36
	v_sqrt_f32_e32 v38, v15
	v_cndmask_b32_e64 v36, v36, v37, s[0:1]
	v_sqrt_f32_e32 v37, v36
	v_add_u32_e32 v39, -1, v38
	v_add_u32_e32 v40, 1, v38
	v_fma_f32 v41, -v39, v38, v15
	v_fma_f32 v42, -v40, v38, v15
	v_add_u32_e32 v43, -1, v37
	v_cmp_ge_f32_e64 s[4:5], 0, v41
	v_add_u32_e32 v44, 1, v37
	v_fma_f32 v41, -v44, v37, v36
	v_cndmask_b32_e64 v38, v38, v39, s[4:5]
	v_fma_f32 v39, -v43, v37, v36
	v_cmp_lt_f32_e64 s[4:5], 0, v42
	s_nop 1
	v_cndmask_b32_e64 v38, v38, v40, s[4:5]
	v_cmp_ge_f32_e64 s[4:5], 0, v39
	v_mul_f32_e32 v39, 0x37800000, v38
	v_cndmask_b32_e32 v38, v38, v39, vcc
	v_cndmask_b32_e64 v37, v37, v43, s[4:5]
	v_cmp_lt_f32_e64 s[4:5], 0, v41
	v_cmp_class_f32_e32 vcc, v15, v14
	s_nop 0
	v_cndmask_b32_e64 v37, v37, v44, s[4:5]
	v_mul_f32_e32 v39, 0x37800000, v37
	v_cndmask_b32_e32 v15, v38, v15, vcc
	v_cndmask_b32_e64 v37, v37, v39, s[0:1]
	v_cmp_class_f32_e32 vcc, v36, v14
	v_div_scale_f32 v38, s[0:1], v15, v15, s29
	s_nop 0
	v_cndmask_b32_e32 v37, v37, v36, vcc
	v_rcp_f32_e32 v36, v38
	v_div_scale_f32 v40, s[4:5], v37, v37, s29
	v_rcp_f32_e32 v42, v40
	v_fma_f32 v43, -v38, v36, 1.0
	v_div_scale_f32 v39, s[0:1], s29, v15, s29
	v_fmac_f32_e32 v36, v43, v36
	v_fma_f32 v43, -v40, v42, 1.0
	v_div_scale_f32 v41, s[4:5], s29, v37, s29
	v_mul_f32_e32 v44, v39, v36
	v_fmac_f32_e32 v42, v43, v42
	v_fma_f32 v43, -v38, v44, v39
	v_mul_f32_e32 v45, v41, v42
	v_fmac_f32_e32 v44, v43, v36
	v_fma_f32 v43, -v40, v45, v41
	v_fma_f32 v38, -v38, v44, v39
	v_fmac_f32_e32 v45, v43, v42
	s_mov_b64 vcc, s[0:1]
	v_div_fmas_f32 v36, v38, v36, v44
	v_fma_f32 v38, -v40, v45, v41
	s_mov_b64 vcc, s[4:5]
	v_div_fixup_f32 v36, v36, v15, s29
	v_div_fmas_f32 v15, v38, v42, v45
	v_pk_mul_f32 v[20:21], v[20:21], v[36:37] op_sel_hi:[1,0]
	v_pk_mul_f32 v[16:17], v[16:17], v[36:37] op_sel_hi:[1,0]
	v_pk_mul_f32 v[22:23], v[22:23], v[36:37] op_sel_hi:[1,0]
	v_pk_mul_f32 v[18:19], v[18:19], v[36:37] op_sel_hi:[1,0]
	v_div_fixup_f32 v36, v15, v37, s29
	v_pk_mul_f32 v[38:39], v[6:7], v[16:17]
	v_pk_mul_f32 v[16:17], v[4:5], v[20:21]
	v_pk_mul_f32 v[20:21], v[2:3], v[18:19]
	v_pk_mul_f32 v[18:19], v[0:1], v[22:23]
	v_pk_mul_f32 v[22:23], v[28:29], v[36:37] op_sel_hi:[1,0]
	v_pk_mul_f32 v[24:25], v[24:25], v[36:37] op_sel_hi:[1,0]
	v_pk_mul_f32 v[28:29], v[30:31], v[36:37] op_sel_hi:[1,0]
	v_pk_mul_f32 v[26:27], v[26:27], v[36:37] op_sel_hi:[1,0]
	v_cvt_pk_bf16_f32 v16, v16, v17
	v_cvt_pk_bf16_f32 v17, v38, v39
	v_cvt_pk_bf16_f32 v18, v18, v19
	v_cvt_pk_bf16_f32 v19, v20, v21
	v_pk_mul_f32 v[20:21], v[6:7], v[24:25]
	v_pk_mul_f32 v[22:23], v[4:5], v[22:23]
	v_pk_mul_f32 v[24:25], v[2:3], v[26:27]
	v_pk_mul_f32 v[26:27], v[0:1], v[28:29]
	global_store_dwordx4 v[32:33], v[16:19], off
	s_nop 1
	v_cvt_pk_bf16_f32 v16, v22, v23
	v_cvt_pk_bf16_f32 v17, v20, v21
	v_cvt_pk_bf16_f32 v18, v26, v27
	v_cvt_pk_bf16_f32 v19, v24, v25
	global_store_dwordx4 v[34:35], v[16:19], off
	s_cbranch_scc1 .LBB0_571

.LBB0_578:
	v_add_u32_e32 v15, s13, v12
	v_mad_i64_i32 v[32:33], s[0:1], v15, s14, v[8:9]
	v_add_u32_e32 v15, 4, v15
	global_load_dwordx4 v[16:19], v[32:33], off
	global_load_dwordx4 v[20:23], v[32:33], off offset:1024
	v_mad_i64_i32 v[34:35], s[0:1], v15, s14, v[8:9]
	global_load_dwordx4 v[24:27], v[34:35], off
	global_load_dwordx4 v[28:31], v[34:35], off offset:1024
	s_add_i32 s13, s13, 8
	s_cmp_lg_u32 s13, 32
	s_waitcnt vmcnt(3)
	v_lshlrev_b32_e32 v36, 16, v16
	v_and_b32_e32 v37, 0xffff0000, v16
	v_lshlrev_b32_e32 v16, 16, v17
	v_and_b32_e32 v17, 0xffff0000, v17
	s_waitcnt vmcnt(2)
	v_lshlrev_b32_e32 v38, 16, v20
	v_and_b32_e32 v39, 0xffff0000, v20
	v_lshlrev_b32_e32 v20, 16, v21
	v_and_b32_e32 v21, 0xffff0000, v21
	v_lshlrev_b32_e32 v40, 16, v18
	v_and_b32_e32 v41, 0xffff0000, v18
	v_lshlrev_b32_e32 v18, 16, v19
	v_and_b32_e32 v19, 0xffff0000, v19
	v_lshlrev_b32_e32 v42, 16, v22
	v_and_b32_e32 v43, 0xffff0000, v22
	v_lshlrev_b32_e32 v22, 16, v23
	v_and_b32_e32 v23, 0xffff0000, v23
	v_pk_fma_f32 v[16:17], s[10:11], v[20:21], v[16:17]
	v_pk_fma_f32 v[20:21], s[6:7], v[38:39], v[36:37] neg_lo:[1,0,0] neg_hi:[1,0,0]
	v_pk_fma_f32 v[18:19], s[10:11], v[22:23], v[18:19]
	v_pk_fma_f32 v[22:23], s[6:7], v[42:43], v[40:41] neg_lo:[1,0,0] neg_hi:[1,0,0]
	s_waitcnt vmcnt(1)
	v_lshlrev_b32_e32 v36, 16, v24
	v_and_b32_e32 v37, 0xffff0000, v24
	v_lshlrev_b32_e32 v24, 16, v25
	v_and_b32_e32 v25, 0xffff0000, v25
	s_waitcnt vmcnt(0)
	v_lshlrev_b32_e32 v38, 16, v28
	v_and_b32_e32 v39, 0xffff0000, v28
	v_lshlrev_b32_e32 v28, 16, v29
	v_and_b32_e32 v29, 0xffff0000, v29
	v_pk_mul_f32 v[44:45], v[16:17], v[16:17]
	v_pk_mul_f32 v[46:47], v[20:21], v[20:21]
	v_lshlrev_b32_e32 v40, 16, v26
	v_and_b32_e32 v41, 0xffff0000, v26
	v_lshlrev_b32_e32 v26, 16, v27
	v_and_b32_e32 v27, 0xffff0000, v27
	v_lshlrev_b32_e32 v42, 16, v30
	v_and_b32_e32 v43, 0xffff0000, v30
	v_lshlrev_b32_e32 v30, 16, v31
	v_and_b32_e32 v31, 0xffff0000, v31
	v_pk_mul_f32 v[48:49], v[18:19], v[18:19]
	v_pk_mul_f32 v[50:51], v[22:23], v[22:23]
	v_pk_fma_f32 v[24:25], s[10:11], v[28:29], v[24:25]
	v_pk_fma_f32 v[28:29], s[6:7], v[38:39], v[36:37] neg_lo:[1,0,0] neg_hi:[1,0,0]
	v_pk_mov_b32 v[36:37], v[46:47], v[44:45] op_sel:[1,0]
	v_mov_b32_e32 v47, v45
	v_pk_fma_f32 v[26:27], s[10:11], v[30:31], v[26:27]
	v_pk_fma_f32 v[30:31], s[6:7], v[42:43], v[40:41] neg_lo:[1,0,0] neg_hi:[1,0,0]
	v_mov_b32_e32 v38, v48
	v_mov_b32_e32 v39, v50
	v_mov_b32_e32 v50, v49
	v_pk_mul_f32 v[40:41], v[24:25], v[24:25]
	v_pk_mul_f32 v[42:43], v[28:29], v[28:29]
	v_pk_add_f32 v[36:37], v[36:37], v[46:47]
	v_pk_mul_f32 v[44:45], v[26:27], v[26:27]
	v_pk_mul_f32 v[48:49], v[30:31], v[30:31]
	v_pk_add_f32 v[38:39], v[38:39], v[50:51]
	v_pk_mov_b32 v[46:47], v[42:43], v[40:41] op_sel:[1,0]
	v_mov_b32_e32 v43, v41
	v_add_f32_e32 v15, v36, v37
	v_mov_b32_e32 v40, v44
	v_mov_b32_e32 v41, v48
	v_mov_b32_e32 v48, v45
	v_pk_add_f32 v[36:37], v[46:47], v[42:43]
	v_add_f32_e32 v15, v39, v15
	v_pk_add_f32 v[40:41], v[40:41], v[48:49]
	v_add_f32_e32 v36, v36, v37
	v_add_f32_e32 v15, v38, v15
	v_add_f32_e32 v36, v41, v36
	v_add_f32_e32 v36, v40, v36
	s_nop 1
	v_add_f32_dpp v15, v15, v15 quad_perm:[1,0,3,2] row_mask:0xf bank_mask:0xf
	v_add_f32_dpp v36, v36, v36 quad_perm:[1,0,3,2] row_mask:0xf bank_mask:0xf
	s_nop 0
	v_add_f32_dpp v15, v15, v15 quad_perm:[2,3,0,1] row_mask:0xf bank_mask:0xf
	v_add_f32_dpp v36, v36, v36 quad_perm:[2,3,0,1] row_mask:0xf bank_mask:0xf
	s_nop 0
	v_add_f32_dpp v15, v15, v15 row_half_mirror row_mask:0xf bank_mask:0xf
	v_add_f32_dpp v36, v36, v36 row_half_mirror row_mask:0xf bank_mask:0xf
	s_nop 0
	v_add_f32_dpp v15, v15, v15 row_mirror row_mask:0xf bank_mask:0xf
	v_add_f32_dpp v36, v36, v36 row_mirror row_mask:0xf bank_mask:0xf
	s_nop 0
	v_fmamk_f32 v15, v15, 0x3c000000, v13
	v_mul_f32_e32 v37, 0x4f800000, v15
	v_cmp_gt_f32_e32 vcc, s15, v15
	v_fmamk_f32 v36, v36, 0x3c000000, v13
	v_cmp_gt_f32_e64 s[0:1], s15, v36
	v_cndmask_b32_e32 v15, v15, v37, vcc
	v_mul_f32_e32 v37, 0x4f800000, v36
	v_sqrt_f32_e32 v38, v15
	v_cndmask_b32_e64 v36, v36, v37, s[0:1]
	v_sqrt_f32_e32 v37, v36
	v_add_u32_e32 v39, -1, v38
	v_add_u32_e32 v40, 1, v38
	v_fma_f32 v41, -v39, v38, v15
	v_fma_f32 v42, -v40, v38, v15
	v_add_u32_e32 v43, -1, v37
	v_cmp_ge_f32_e64 s[4:5], 0, v41
	v_add_u32_e32 v44, 1, v37
	v_fma_f32 v41, -v44, v37, v36
	v_cndmask_b32_e64 v38, v38, v39, s[4:5]
	v_fma_f32 v39, -v43, v37, v36
	v_cmp_lt_f32_e64 s[4:5], 0, v42
	s_nop 1
	v_cndmask_b32_e64 v38, v38, v40, s[4:5]
	v_cmp_ge_f32_e64 s[4:5], 0, v39
	v_mul_f32_e32 v39, 0x37800000, v38
	v_cndmask_b32_e32 v38, v38, v39, vcc
	v_cndmask_b32_e64 v37, v37, v43, s[4:5]
	v_cmp_lt_f32_e64 s[4:5], 0, v41
	v_cmp_class_f32_e32 vcc, v15, v14
	s_nop 0
	v_cndmask_b32_e64 v37, v37, v44, s[4:5]
	v_mul_f32_e32 v39, 0x37800000, v37
	v_cndmask_b32_e32 v15, v38, v15, vcc
	v_cndmask_b32_e64 v37, v37, v39, s[0:1]
	v_cmp_class_f32_e32 vcc, v36, v14
	v_div_scale_f32 v38, s[0:1], v15, v15, s20
	s_nop 0
	v_cndmask_b32_e32 v37, v37, v36, vcc
	v_rcp_f32_e32 v36, v38
	v_div_scale_f32 v40, s[4:5], v37, v37, s20
	v_rcp_f32_e32 v42, v40
	v_fma_f32 v43, -v38, v36, 1.0
	v_div_scale_f32 v39, s[0:1], s20, v15, s20
	v_fmac_f32_e32 v36, v43, v36
	v_fma_f32 v43, -v40, v42, 1.0
	v_div_scale_f32 v41, s[4:5], s20, v37, s20
	v_mul_f32_e32 v44, v39, v36
	v_fmac_f32_e32 v42, v43, v42
	v_fma_f32 v43, -v38, v44, v39
	v_mul_f32_e32 v45, v41, v42
	v_fmac_f32_e32 v44, v43, v36
	v_fma_f32 v43, -v40, v45, v41
	v_fma_f32 v38, -v38, v44, v39
	v_fmac_f32_e32 v45, v43, v42
	s_mov_b64 vcc, s[0:1]
	v_div_fmas_f32 v36, v38, v36, v44
	v_fma_f32 v38, -v40, v45, v41
	s_mov_b64 vcc, s[4:5]
	v_div_fixup_f32 v36, v36, v15, s20
	v_div_fmas_f32 v15, v38, v42, v45
	v_pk_mul_f32 v[20:21], v[20:21], v[36:37] op_sel_hi:[1,0]
	v_pk_mul_f32 v[16:17], v[16:17], v[36:37] op_sel_hi:[1,0]
	v_pk_mul_f32 v[22:23], v[22:23], v[36:37] op_sel_hi:[1,0]
	v_pk_mul_f32 v[18:19], v[18:19], v[36:37] op_sel_hi:[1,0]
	v_div_fixup_f32 v36, v15, v37, s20
	v_pk_mul_f32 v[38:39], v[6:7], v[16:17]
	v_pk_mul_f32 v[16:17], v[4:5], v[20:21]
	v_pk_mul_f32 v[20:21], v[2:3], v[18:19]
	v_pk_mul_f32 v[18:19], v[0:1], v[22:23]
	v_pk_mul_f32 v[22:23], v[28:29], v[36:37] op_sel_hi:[1,0]
	v_pk_mul_f32 v[24:25], v[24:25], v[36:37] op_sel_hi:[1,0]
	v_pk_mul_f32 v[28:29], v[30:31], v[36:37] op_sel_hi:[1,0]
	v_pk_mul_f32 v[26:27], v[26:27], v[36:37] op_sel_hi:[1,0]
	v_cvt_pk_bf16_f32 v16, v16, v17
	v_cvt_pk_bf16_f32 v17, v38, v39
	v_cvt_pk_bf16_f32 v18, v18, v19
	v_cvt_pk_bf16_f32 v19, v20, v21
	v_pk_mul_f32 v[20:21], v[6:7], v[24:25]
	v_pk_mul_f32 v[22:23], v[4:5], v[22:23]
	v_pk_mul_f32 v[24:25], v[2:3], v[26:27]
	v_pk_mul_f32 v[26:27], v[0:1], v[28:29]
	global_store_dwordx4 v[32:33], v[16:19], off
	s_nop 1
	v_cvt_pk_bf16_f32 v16, v22, v23
	v_cvt_pk_bf16_f32 v17, v20, v21
	v_cvt_pk_bf16_f32 v18, v26, v27
	v_cvt_pk_bf16_f32 v19, v24, v25
	global_store_dwordx4 v[34:35], v[16:19], off
	s_cbranch_scc1 .LBB0_578

.LBB0_585:
	v_add_u32_e32 v13, s12, v10
	v_mad_i64_i32 v[30:31], s[0:1], v13, s3, v[8:9]
	v_add_u32_e32 v13, 4, v13
	global_load_dwordx4 v[14:17], v[30:31], off
	global_load_dwordx4 v[18:21], v[30:31], off offset:1024
	v_mad_i64_i32 v[32:33], s[0:1], v13, s3, v[8:9]
	global_load_dwordx4 v[22:25], v[32:33], off
	global_load_dwordx4 v[26:29], v[32:33], off offset:1024
	s_add_i32 s12, s12, 8
	s_cmp_lg_u32 s12, 32
	s_waitcnt vmcnt(3)
	v_lshlrev_b32_e32 v34, 16, v14
	v_and_b32_e32 v35, 0xffff0000, v14
	v_lshlrev_b32_e32 v14, 16, v15
	v_and_b32_e32 v15, 0xffff0000, v15
	s_waitcnt vmcnt(2)
	v_lshlrev_b32_e32 v36, 16, v18
	v_and_b32_e32 v37, 0xffff0000, v18
	v_lshlrev_b32_e32 v18, 16, v19
	v_and_b32_e32 v19, 0xffff0000, v19
	v_lshlrev_b32_e32 v38, 16, v16
	v_and_b32_e32 v39, 0xffff0000, v16
	v_lshlrev_b32_e32 v16, 16, v17
	v_and_b32_e32 v17, 0xffff0000, v17
	v_lshlrev_b32_e32 v40, 16, v20
	v_and_b32_e32 v41, 0xffff0000, v20
	v_lshlrev_b32_e32 v20, 16, v21
	v_and_b32_e32 v21, 0xffff0000, v21
	v_pk_fma_f32 v[14:15], s[10:11], v[18:19], v[14:15]
	v_pk_fma_f32 v[18:19], s[6:7], v[36:37], v[34:35] neg_lo:[1,0,0] neg_hi:[1,0,0]
	v_pk_fma_f32 v[16:17], s[10:11], v[20:21], v[16:17]
	v_pk_fma_f32 v[20:21], s[6:7], v[40:41], v[38:39] neg_lo:[1,0,0] neg_hi:[1,0,0]
	s_waitcnt vmcnt(1)
	v_lshlrev_b32_e32 v34, 16, v22
	v_and_b32_e32 v35, 0xffff0000, v22
	v_lshlrev_b32_e32 v22, 16, v23
	v_and_b32_e32 v23, 0xffff0000, v23
	s_waitcnt vmcnt(0)
	v_lshlrev_b32_e32 v36, 16, v26
	v_and_b32_e32 v37, 0xffff0000, v26
	v_lshlrev_b32_e32 v26, 16, v27
	v_and_b32_e32 v27, 0xffff0000, v27
	v_pk_mul_f32 v[42:43], v[14:15], v[14:15]
	v_pk_mul_f32 v[44:45], v[18:19], v[18:19]
	v_lshlrev_b32_e32 v38, 16, v24
	v_and_b32_e32 v39, 0xffff0000, v24
	v_lshlrev_b32_e32 v24, 16, v25
	v_and_b32_e32 v25, 0xffff0000, v25
	v_lshlrev_b32_e32 v40, 16, v28
	v_and_b32_e32 v41, 0xffff0000, v28
	v_lshlrev_b32_e32 v28, 16, v29
	v_and_b32_e32 v29, 0xffff0000, v29
	v_pk_mul_f32 v[46:47], v[16:17], v[16:17]
	v_pk_mul_f32 v[48:49], v[20:21], v[20:21]
	v_pk_fma_f32 v[22:23], s[10:11], v[26:27], v[22:23]
	v_pk_fma_f32 v[26:27], s[6:7], v[36:37], v[34:35] neg_lo:[1,0,0] neg_hi:[1,0,0]
	v_pk_mov_b32 v[34:35], v[44:45], v[42:43] op_sel:[1,0]
	v_mov_b32_e32 v45, v43
	v_pk_fma_f32 v[24:25], s[10:11], v[28:29], v[24:25]
	v_pk_fma_f32 v[28:29], s[6:7], v[40:41], v[38:39] neg_lo:[1,0,0] neg_hi:[1,0,0]
	v_mov_b32_e32 v36, v46
	v_mov_b32_e32 v37, v48
	v_mov_b32_e32 v48, v47
	v_pk_mul_f32 v[38:39], v[22:23], v[22:23]
	v_pk_mul_f32 v[40:41], v[26:27], v[26:27]
	v_pk_add_f32 v[34:35], v[34:35], v[44:45]
	v_pk_mul_f32 v[42:43], v[24:25], v[24:25]
	v_pk_mul_f32 v[46:47], v[28:29], v[28:29]
	v_pk_add_f32 v[36:37], v[36:37], v[48:49]
	v_pk_mov_b32 v[44:45], v[40:41], v[38:39] op_sel:[1,0]
	v_mov_b32_e32 v41, v39
	v_add_f32_e32 v13, v34, v35
	v_mov_b32_e32 v38, v42
	v_mov_b32_e32 v39, v46
	v_mov_b32_e32 v46, v43
	v_pk_add_f32 v[34:35], v[44:45], v[40:41]
	v_add_f32_e32 v13, v37, v13
	v_pk_add_f32 v[38:39], v[38:39], v[46:47]
	v_add_f32_e32 v34, v34, v35
	v_add_f32_e32 v13, v36, v13
	v_add_f32_e32 v34, v39, v34
	v_add_f32_e32 v34, v38, v34
	s_nop 1
	v_add_f32_dpp v13, v13, v13 quad_perm:[1,0,3,2] row_mask:0xf bank_mask:0xf
	v_add_f32_dpp v34, v34, v34 quad_perm:[1,0,3,2] row_mask:0xf bank_mask:0xf
	s_nop 0
	v_add_f32_dpp v13, v13, v13 quad_perm:[2,3,0,1] row_mask:0xf bank_mask:0xf
	v_add_f32_dpp v34, v34, v34 quad_perm:[2,3,0,1] row_mask:0xf bank_mask:0xf
	s_nop 0
	v_add_f32_dpp v13, v13, v13 row_half_mirror row_mask:0xf bank_mask:0xf
	v_add_f32_dpp v34, v34, v34 row_half_mirror row_mask:0xf bank_mask:0xf
	s_nop 0
	v_add_f32_dpp v13, v13, v13 row_mirror row_mask:0xf bank_mask:0xf
	v_add_f32_dpp v34, v34, v34 row_mirror row_mask:0xf bank_mask:0xf
	s_nop 0
	v_fmamk_f32 v13, v13, 0x3c000000, v11
	v_mul_f32_e32 v35, 0x4f800000, v13
	v_cmp_gt_f32_e32 vcc, s13, v13
	v_fmamk_f32 v34, v34, 0x3c000000, v11
	v_cmp_gt_f32_e64 s[0:1], s13, v34
	v_cndmask_b32_e32 v13, v13, v35, vcc
	v_mul_f32_e32 v35, 0x4f800000, v34
	v_sqrt_f32_e32 v36, v13
	v_cndmask_b32_e64 v34, v34, v35, s[0:1]
	v_sqrt_f32_e32 v35, v34
	v_add_u32_e32 v37, -1, v36
	v_add_u32_e32 v38, 1, v36
	v_fma_f32 v39, -v37, v36, v13
	v_fma_f32 v40, -v38, v36, v13
	v_add_u32_e32 v41, -1, v35
	v_cmp_ge_f32_e64 s[4:5], 0, v39
	v_add_u32_e32 v42, 1, v35
	v_fma_f32 v39, -v42, v35, v34
	v_cndmask_b32_e64 v36, v36, v37, s[4:5]
	v_fma_f32 v37, -v41, v35, v34
	v_cmp_lt_f32_e64 s[4:5], 0, v40
	s_nop 1
	v_cndmask_b32_e64 v36, v36, v38, s[4:5]
	v_cmp_ge_f32_e64 s[4:5], 0, v37
	v_mul_f32_e32 v37, 0x37800000, v36
	v_cndmask_b32_e32 v36, v36, v37, vcc
	v_cndmask_b32_e64 v35, v35, v41, s[4:5]
	v_cmp_lt_f32_e64 s[4:5], 0, v39
	v_cmp_class_f32_e32 vcc, v13, v12
	s_nop 0
	v_cndmask_b32_e64 v35, v35, v42, s[4:5]
	v_mul_f32_e32 v37, 0x37800000, v35
	v_cndmask_b32_e32 v13, v36, v13, vcc
	v_cndmask_b32_e64 v35, v35, v37, s[0:1]
	v_cmp_class_f32_e32 vcc, v34, v12
	v_div_scale_f32 v36, s[0:1], v13, v13, s14
	s_nop 0
	v_cndmask_b32_e32 v35, v35, v34, vcc
	v_rcp_f32_e32 v34, v36
	v_div_scale_f32 v38, s[4:5], v35, v35, s14
	v_rcp_f32_e32 v40, v38
	v_fma_f32 v41, -v36, v34, 1.0
	v_div_scale_f32 v37, s[0:1], s14, v13, s14
	v_fmac_f32_e32 v34, v41, v34
	v_fma_f32 v41, -v38, v40, 1.0
	v_div_scale_f32 v39, s[4:5], s14, v35, s14
	v_mul_f32_e32 v42, v37, v34
	v_fmac_f32_e32 v40, v41, v40
	v_fma_f32 v41, -v36, v42, v37
	v_mul_f32_e32 v43, v39, v40
	v_fmac_f32_e32 v42, v41, v34
	v_fma_f32 v41, -v38, v43, v39
	v_fma_f32 v36, -v36, v42, v37
	v_fmac_f32_e32 v43, v41, v40
	s_mov_b64 vcc, s[0:1]
	v_div_fmas_f32 v34, v36, v34, v42
	v_fma_f32 v36, -v38, v43, v39
	s_mov_b64 vcc, s[4:5]
	v_div_fixup_f32 v34, v34, v13, s14
	v_div_fmas_f32 v13, v36, v40, v43
	v_pk_mul_f32 v[18:19], v[18:19], v[34:35] op_sel_hi:[1,0]
	v_pk_mul_f32 v[14:15], v[14:15], v[34:35] op_sel_hi:[1,0]
	v_pk_mul_f32 v[20:21], v[20:21], v[34:35] op_sel_hi:[1,0]
	v_pk_mul_f32 v[16:17], v[16:17], v[34:35] op_sel_hi:[1,0]
	v_div_fixup_f32 v34, v13, v35, s14
	v_pk_mul_f32 v[36:37], v[6:7], v[14:15]
	v_pk_mul_f32 v[14:15], v[4:5], v[18:19]
	v_pk_mul_f32 v[18:19], v[2:3], v[16:17]
	v_pk_mul_f32 v[16:17], v[0:1], v[20:21]
	v_pk_mul_f32 v[20:21], v[26:27], v[34:35] op_sel_hi:[1,0]
	v_pk_mul_f32 v[22:23], v[22:23], v[34:35] op_sel_hi:[1,0]
	v_pk_mul_f32 v[26:27], v[28:29], v[34:35] op_sel_hi:[1,0]
	v_pk_mul_f32 v[24:25], v[24:25], v[34:35] op_sel_hi:[1,0]
	v_cvt_pk_bf16_f32 v14, v14, v15
	v_cvt_pk_bf16_f32 v15, v36, v37
	v_cvt_pk_bf16_f32 v16, v16, v17
	v_cvt_pk_bf16_f32 v17, v18, v19
	v_pk_mul_f32 v[18:19], v[6:7], v[22:23]
	v_pk_mul_f32 v[20:21], v[4:5], v[20:21]
	v_pk_mul_f32 v[22:23], v[2:3], v[24:25]
	v_pk_mul_f32 v[24:25], v[0:1], v[26:27]
	global_store_dwordx4 v[30:31], v[14:17], off
	s_nop 1
	v_cvt_pk_bf16_f32 v14, v20, v21
	v_cvt_pk_bf16_f32 v15, v18, v19
	v_cvt_pk_bf16_f32 v16, v24, v25
	v_cvt_pk_bf16_f32 v17, v22, v23
	global_store_dwordx4 v[32:33], v[14:17], off
	s_cbranch_scc1 .LBB0_585
